# MoBA: LDS-DMA K/V rings (XOR-swizzled, prefetch distance 2) + half-tile stagger between wave halves (waves 4-7 defer PV by one tile)
# speedup vs baseline: 1.0097x; 1.0005x over previous
; __device__ __forceinline__ int tid_opaque() { int t = threadIdx.x; asm volatile("" : "+v"(t)); return t; }
; __device__ __forceinline__ void phase_moba_mfma(const Params& p, LAS unsigned char* lds, unsigned lds_base) {
;     ...
;     const int tid = tid_opaque(), lane = tid & 63, wave = __builtin_amdgcn_readfirstlane(tid >> 6);
;     const int i32 = lane & 31, hh = lane >> 5;
;     bf16_t* MBQ = (bf16_t*)(p.ws + WS_MB); const bf16_t* MBK = MBQ + (size_t)M_ * D_; const bf16_t* MBV = MBK + (size_t)M_ * D_;
;     const float* KM = (const float*)(p.ws + WS_KMEAN); const float* BT = (const float*)(p.ws + WS_BT);
;     const int G = gridDim.x, cblk = blockIdx.x;
;     const int lrow = tid >> 3, lc = tid & 7;
;     const unsigned vbase = lds_base + OFF_V + (4 * hh + ((lane & 15) >> 2)) * VST + (16 * ((lane >> 4) & 1) + 4 * (lane & 3)) * 2;
;     const float NINF = -__builtin_inff();
.LBB0_732:
	s_add_u32 s22, s26, 0x1e408000
	s_addc_u32 s23, s27, 0
	s_add_u32 s34, s26, 0x22408000
	s_addc_u32 s35, s27, 0
	v_readlane_b32 s65, v253, 5
	v_mov_b32_e32 v179, v247
	s_cmpk_gt_i32 s65, 0x3ff
	s_waitcnt lgkmcnt(0)
	s_barrier
	s_nop 0
	v_readfirstlane_b32 s0, v179
	s_cbranch_scc1 .LBB0_763
	s_waitcnt vmcnt(10)
	v_mbcnt_hi_u32_b32 v11, -1, v252
	s_waitcnt vmcnt(9)
	v_and_b32_e32 v13, 64, v11
	v_and_b32_e32 v1, 63, v179
	v_xor_b32_e32 v12, 32, v11
	v_add_u32_e32 v13, 64, v13
	v_cmp_lt_i32_e32 vcc, v12, v13
	v_cmp_eq_u32_e64 s[4:5], 0, v1
	v_cmp_gt_u32_e64 s[38:39], 32, v1
	v_xor_b32_e32 v1, 1, v11
	v_cndmask_b32_e32 v12, v11, v12, vcc
	v_cmp_lt_i32_e32 vcc, v1, v13
	s_not_b32 s1, s65
	s_add_i32 s1, s28, s1
	v_cndmask_b32_e32 v1, v11, v1, vcc
	v_lshlrev_b32_e32 v210, 2, v1
	v_xor_b32_e32 v1, 2, v11
	v_cmp_lt_i32_e32 vcc, v1, v13
	v_lshlrev_b32_e32 v5, 2, v179
	v_and_b32_e32 v0, 16, v179
	v_cndmask_b32_e32 v1, v11, v1, vcc
	v_lshlrev_b32_e32 v211, 2, v1
	v_xor_b32_e32 v1, 4, v11
	v_bfe_u32 v4, v179, 5, 1
	s_add_u32 s8, s26, 0xa348000
	v_and_or_b32 v0, v5, 12, v0
	v_cmp_lt_i32_e32 vcc, v1, v13
	v_lshlrev_b32_e32 v180, 2, v4
	s_addc_u32 s9, s27, 0
	v_lshlrev_b32_e32 v6, 1, v0
	v_lshrrev_b32_e32 v0, 2, v179
	s_ashr_i32 s0, s0, 6
	v_cndmask_b32_e32 v1, v11, v1, vcc
	v_writelane_b32 v255, s1, 5
	v_and_or_b32 v0, v0, 3, v180
	v_and_b32_e32 v8, 7, v179
	v_ashrrev_i32_e32 v182, 3, v179
	s_movk_i32 s1, 0x110
	s_lshl_b32 s18, s0, 5
	s_lshl_b32 s0, s0, 2
	v_lshlrev_b32_e32 v212, 2, v1
	v_xor_b32_e32 v1, 8, v11
	v_mul_u32_u24_e32 v7, 0x140, v0
	v_and_b32_e32 v9, 0x7c, v5
	v_mov_b32_e32 v0, 0
	s_add_i32 s2, 16, 0x12800
	v_lshlrev_b32_e32 v193, 2, v12
	v_writelane_b32 v255, s4, 6
	s_add_i32 s0, s0, 16
	v_lshlrev_b32_e32 v190, 4, v8
	v_mul_lo_u32 v12, v182, s1
	v_lshlrev_b32_e32 v8, 5, v8
	v_cmp_lt_i32_e32 vcc, v1, v13
	v_and_b32_e32 v178, 31, v179
	v_ashrrev_i32_e32 v181, 5, v179
	v_lshlrev_b32_e32 v2, 2, v9
	v_mov_b32_e32 v3, v0
	s_add_i32 s3, 16, 0x14a00
	v_mov_b32_e32 v10, s2
	v_writelane_b32 v255, s5, 7
	s_add_i32 s0, s0, 0x15a00
	v_add3_u32 v192, 16, v12, v8
	s_or_b32 s33, s18, 31
	v_cndmask_b32_e32 v1, v11, v1, vcc
	v_lshl_add_u64 v[188:189], s[72:73], 0, v[2:3]
	v_mul_lo_u32 v2, v181, s1
	v_mad_u32_u24 v10, v178, s1, v10
	v_writelane_b32 v255, s0, 8
	v_mad_u64_u32 v[194:195], s[0:1], v182, 48, v[192:193]
	s_cmp_lg_u32 16, -1
	v_lshlrev_b32_e32 v213, 2, v1
	v_xor_b32_e32 v1, 16, v11
	s_cselect_b32 s0, 16, 0
	v_cmp_lt_i32_e32 vcc, v1, v13
	v_add_u32_e32 v3, s2, v2
	v_lshlrev_b32_e32 v9, 1, v9
	v_add_u32_e32 v191, s3, v5
	v_lshlrev_b32_e32 v2, 3, v4
	v_mul_u32_u24_e32 v5, 0x110, v178
	v_lshlrev_b32_e32 v4, 4, v4
	s_add_i32 s0, s0, 0x8800
	v_cndmask_b32_e32 v1, v11, v1, vcc
	s_mov_b32 s2, s65
	s_mov_b32 s69, 0
	v_ashrrev_i32_e32 v183, 31, v182
	v_add3_u32 v195, 16, v5, v4
	v_add3_u32 v207, v6, s0, v7
	v_lshlrev_b32_e32 v214, 2, v1
	v_add_u32_e32 v215, v3, v9
	v_mov_b32_e32 v196, 0
	v_mov_b32_e32 v197, v0
	v_lshlrev_b32_e32 v198, 1, v2
	v_mov_b32_e32 v199, v0
	v_add_u32_e32 v216, v10, v4
	s_mov_b32 s29, 0xff800000
	v_mov_b32_e32 v217, 0xff800000
	s_add_i32 s20, 16, 0x15a10
	v_lshlrev_b32_e32 v200, 1, v180
	s_mov_b32 s21, 0
	v_and_b32_e32 v162, 63, v179
	v_lshrrev_b32_e32 v163, 6, v179
	v_lshrrev_b32_e32 v164, 4, v162
	v_and_b32_e32 v165, 15, v162
	v_lshl_add_u32 v166, v163, 3, v164
	v_and_b32_e32 v167, 15, v166
	v_xor_b32_e32 v167, v165, v167
	v_lshlrev_b32_e32 v167, 4, v167
	v_lshl_add_u32 v224, v166, 12, v167
	v_add_u32_e32 v168, 4, v166
	v_and_b32_e32 v167, 15, v168
	v_xor_b32_e32 v167, v165, v167
	v_lshlrev_b32_e32 v167, 4, v167
	v_lshl_add_u32 v225, v168, 12, v167
	v_lshlrev_b32_e32 v167, 2, v164
	v_xor_b32_e32 v167, v165, v167
	v_lshlrev_b32_e32 v167, 4, v167
	v_lshl_add_u32 v226, v166, 12, v167
	v_lshl_add_u32 v227, v168, 12, v167
	v_and_b32_e32 v166, 31, v162
	v_lshrrev_b32_e32 v167, 5, v162
	v_and_b32_e32 v168, 1, v166
	v_xor_b32_e32 v168, v167, v168
	v_lshlrev_b32_e32 v168, 4, v168
	v_bfe_u32 v169, v166, 1, 3
	v_lshl_or_b32 v168, v169, 5, v168
	v_lshl_or_b32 v228, v166, 8, v168
	v_bfe_u32 v166, v162, 2, 2
	v_bfe_u32 v168, v162, 4, 1
	v_and_b32_e32 v169, 3, v162
	v_lshl_add_u32 v163, v167, 2, v166
	v_lshlrev_b32_e32 v163, 8, v163
	v_lshl_or_b32 v163, v166, 6, v163
	v_lshl_or_b32 v163, v168, 5, v163
	v_lshl_or_b32 v229, v169, 3, v163
	s_branch .LBB0_735

; #define LAS __attribute__((address_space(3)))
; #define MOBA_LOAD(jj, kk) do { const size_t r_ = (rowb + (jj) * 256 + (kk) * 64 + lrow) * D_ + h * 128 + lc * 16; rk0 = *(const u32x4*)(MBK + r_); rk1 = *(const u32x4*)(MBK + r_ + 8); rv0 = *(const u32x4*)(MBV + r_); rv1 = *(const u32x4*)(MBV + r_ + 8); } while (0)
; #define MOBA_STORE(bb) do { LAS unsigned char* kd = lds + OFF_K + (bb) * 64 * KST + lrow * KST + lc * 32; *(LAS u32x4*)kd = rk0; *(LAS u32x4*)(kd + 16) = rk1; \
;         LAS unsigned char* vd = lds + OFF_V + (bb) * 64 * VST + lrow * VST + lc * 32; *(LAS u32x4*)vd = rv0; *(LAS u32x4*)(vd + 16) = rv1; } while (0)
; __device__ __forceinline__ void phase_moba_mfma(const Params& p, LAS unsigned char* lds, unsigned lds_base) {
;     ...
;         unsigned um = 0;
; #pragma unroll
;         for (int w = 0; w < 8; ++w) um |= ((const LAS unsigned*)(lds + OFF_UM))[w];
;         um = __builtin_amdgcn_readfirstlane(um);
;         f32x16 O[4];
; #pragma unroll
;         for (int dt = 0; dt < 4; ++dt)
; #pragma unroll
;             for (int r = 0; r < 16; ++r) O[dt][r] = 0.f;
;         float m = NINF, l = 0.f;
;         int j = qb, kt = 0, buf = 0;
;         u32x4 rk0, rk1, rv0, rv1;
;     ...
;         MOBA_LOAD(j, kt); MOBA_STORE(0); __syncthreads();
;         while (j >= 0) {
;             int nj = j, nkt = kt + 1;
;     ...
;             if (nj >= 0) MOBA_LOAD(nj, nkt);
.LBB0_737:
	s_or_b64 exec, exec, s[0:1]
	s_add_i32 s0, 16, 0x15a00
	v_mov_b32_e32 v16, s0
	s_waitcnt lgkmcnt(0)
	s_barrier
	ds_read_b128 v[16:19], v16
	s_lshl_b32 s4, s11, 7
	s_add_u32 s0, s7, s10
	s_addc_u32 s1, 0, 0
	v_or_b32_e32 v206, s4, v190
	s_waitcnt lgkmcnt(0)
	v_or_b32_e32 v16, v17, v16
	v_or_b32_e32 v16, v16, v18
	v_or_b32_e32 v20, v16, v19
	v_mov_b32_e32 v16, s20
	ds_read_b128 v[16:19], v16
	v_mov_b64_e32 v[64:65], v[14:15]
	v_mov_b64_e32 v[48:49], v[14:15]
	v_mov_b64_e32 v[62:63], v[12:13]
	v_mov_b64_e32 v[60:61], v[10:11]
	s_waitcnt lgkmcnt(0)
	v_or_b32_e32 v16, v20, v16
	v_or_b32_e32 v16, v16, v17
	v_or_b32_e32 v16, v16, v18
	v_or_b32_e32 v16, v16, v19
	v_mov_b64_e32 v[58:59], v[8:9]
	v_readfirstlane_b32 s68, v16
	s_lshl_b32 s46, s4, 1
	v_mov_b32_e32 v174, s46
	s_mov_b32 s46, s0
	s_mov_b32 s48, s0
	s_mov_b32 s0, s48
	s_lshl_b32 s0, s0, 12
	v_readfirstlane_b32 s1, v174
	s_nop 0
	s_add_i32 s0, s0, s1
	s_add_u32 s40, s22, s0
	s_addc_u32 s41, s23, 0
	s_add_u32 s42, s34, s0
	s_addc_u32 s43, s35, 0
	s_mov_b32 s44, 0
	s_mov_b32 s47, 0xc000
	s_lshl_b32 s45, s18, 6
	s_add_i32 s44, s44, s45
	s_add_i32 s44, s44, 16
	s_add_i32 s47, s47, s45
	s_add_i32 s47, s47, 16
	s_mov_b32 m0, s44
	s_nop 0
	global_load_lds_dwordx4 v224, s[40:41]
	s_add_i32 m0, s44, 0x400
	s_nop 0
	global_load_lds_dwordx4 v225, s[40:41]
	s_mov_b32 m0, s47
	s_nop 0
	global_load_lds_dwordx4 v226, s[42:43]
	s_add_i32 m0, s47, 0x400
	s_nop 0
	global_load_lds_dwordx4 v227, s[42:43]
	s_add_i32 s48, s48, 64
	s_mov_b32 s0, s48
	s_lshl_b32 s0, s0, 12
	v_readfirstlane_b32 s1, v174
	s_nop 0
	s_add_i32 s0, s0, s1
	s_add_u32 s40, s22, s0
	s_addc_u32 s41, s23, 0
	s_add_u32 s42, s34, s0
	s_addc_u32 s43, s35, 0
	s_mov_b32 s44, 0x4000
	s_mov_b32 s47, 0x16000
	s_lshl_b32 s45, s18, 6
	s_add_i32 s44, s44, s45
	s_add_i32 s44, s44, 16
	s_add_i32 s47, s47, s45
	s_add_i32 s47, s47, 16
	s_mov_b32 m0, s44
	s_nop 0
	global_load_lds_dwordx4 v224, s[40:41]
	s_add_i32 m0, s44, 0x400
	s_nop 0
	global_load_lds_dwordx4 v225, s[40:41]
	s_mov_b32 m0, s47
	s_nop 0
	global_load_lds_dwordx4 v226, s[42:43]
	s_add_i32 m0, s47, 0x400
	s_nop 0
	global_load_lds_dwordx4 v227, s[42:43]
	v_mov_b64_e32 v[32:33], v[14:15]
	v_mov_b64_e32 v[56:57], v[6:7]
	v_mov_b64_e32 v[54:55], v[4:5]
	v_mov_b64_e32 v[52:53], v[2:3]
	v_mov_b64_e32 v[50:51], v[0:1]
	v_mov_b64_e32 v[46:47], v[12:13]
	v_mov_b64_e32 v[44:45], v[10:11]
	v_mov_b64_e32 v[42:43], v[8:9]
	v_mov_b64_e32 v[40:41], v[6:7]
	v_mov_b64_e32 v[38:39], v[4:5]
	v_mov_b64_e32 v[36:37], v[2:3]
	v_mov_b64_e32 v[34:35], v[0:1]
	v_mov_b64_e32 v[30:31], v[12:13]
	v_mov_b64_e32 v[28:29], v[10:11]
	v_mov_b64_e32 v[26:27], v[8:9]
	v_mov_b64_e32 v[24:25], v[6:7]
	v_mov_b64_e32 v[22:23], v[4:5]
	v_mov_b64_e32 v[20:21], v[2:3]
	v_mov_b64_e32 v[18:19], v[0:1]
	v_mov_b64_e32 v[16:17], v[14:15]
	s_and_b32 s7, s2, 48
	v_or_b32_e32 v218, s6, v178
	s_mov_b32 s37, 0
	s_waitcnt vmcnt(4)
	v_mov_b32_e32 v208, v204
	v_mov_b32_e32 v209, v204
	v_mov_b32_e32 v220, 0xff800000
	v_mov_b32_e32 v219, 0
	v_mov_b64_e32 v[14:15], v[12:13]
	v_mov_b64_e32 v[12:13], v[10:11]
	v_mov_b64_e32 v[10:11], v[8:9]
	v_mov_b64_e32 v[8:9], v[6:7]
	v_mov_b64_e32 v[6:7], v[4:5]
	v_mov_b64_e32 v[4:5], v[2:3]
	v_mov_b64_e32 v[2:3], v[0:1]
	s_mov_b32 s19, s36
	s_mov_b32 s2, 0
	s_mov_b32 s10, s36
	s_waitcnt vmcnt(4)
	s_waitcnt lgkmcnt(0)
	s_barrier
	s_mov_b32 s11, 1
	s_mov_b32 s101, 0
	s_mov_b32 s100, 0
	s_branch .Lmoba_top
.Lmoba_top:
	s_cmp_gt_i32 s10, -1
	s_cselect_b64 s[14:15], -1, 0
	s_cmp_lt_i32 s10, 0
	s_cselect_b64 s[12:13], -1, 0
	s_mov_b32 s98, s10
	s_add_i32 s99, s11, 1
	s_cmp_lg_u32 s99, 4
	s_cbranch_scc1 .Lmoba_p2done
.Lmoba_p2scan:
	s_cmp_lt_i32 s98, 1
	s_cbranch_scc1 .Lmoba_p2none
	s_add_i32 s98, s98, -1
	s_lshr_b32 s0, s68, s98
	s_bitcmp1_b32 s0, 0
	s_cbranch_scc0 .Lmoba_p2scan
	s_mov_b32 s99, 0
	s_branch .Lmoba_p2done
.Lmoba_p2none:
	s_mov_b32 s98, -1
	s_mov_b32 s99, 0
.Lmoba_p2done:
	s_cmp_lt_i32 s98, 0
	s_cbranch_scc1 .LBB0_744
	s_add_i32 s0, s98, s7
	s_lshl_b32 s0, s0, 8
	s_lshl_b32 s1, s99, 6
	s_add_i32 s0, s0, s1
	s_lshl_b32 s0, s0, 12
	v_readfirstlane_b32 s1, v174
	s_nop 0
	s_add_i32 s0, s0, s1
	s_add_u32 s40, s22, s0
	s_addc_u32 s41, s23, 0
	s_add_u32 s42, s34, s0
	s_addc_u32 s43, s35, 0
	s_add_i32 s44, s101, 2
	s_cmp_gt_u32 s44, 2
	s_cselect_b32 s45, 3, 0
	s_sub_i32 s44, s44, s45
	s_lshl_b32 s44, s44, 14
	s_add_i32 s46, s100, 2
	s_and_b32 s46, s46, 3
	s_lshl_b32 s47, s46, 14
	s_add_i32 s47, s47, 0x12000
	s_cmp_eq_u32 s46, 0
	s_cselect_b32 s47, 0xc000, s47
	s_lshl_b32 s45, s18, 6
	s_add_i32 s44, s44, s45
	s_add_i32 s44, s44, 16
	s_add_i32 s47, s47, s45
	s_add_i32 s47, s47, 16
	s_mov_b32 m0, s44
	s_nop 0
	global_load_lds_dwordx4 v224, s[40:41]
	s_add_i32 m0, s44, 0x400
	s_nop 0
	global_load_lds_dwordx4 v225, s[40:41]
	s_mov_b32 m0, s47
	s_nop 0
	global_load_lds_dwordx4 v226, s[42:43]
	s_add_i32 m0, s47, 0x400
	s_nop 0
	global_load_lds_dwordx4 v227, s[42:43]

; #define LAS __attribute__((address_space(3)))
; #define MFMA32(a, b, c) __builtin_amdgcn_mfma_f32_32x32x16_bf16((a), (b), (c), 0, 0, 0)
; __device__ __forceinline__ void phase_moba_mfma(const Params& p, LAS unsigned char* lds, unsigned lds_base) {
;     ...
;             if (own) need = (kt * 64 <= 32 * wave + 31); else need = (__ballot((sel >> j) & 1u) != 0ull);
;             if (need) {
;                 const LAS unsigned char* Ks = lds + OFF_K + buf * 64 * KST + i32 * KST + 16 * hh;
;                 f32x16 s0, s1;
; #pragma unroll
;                 for (int r = 0; r < 16; ++r) { s0[r] = 0.f; s1[r] = 0.f; }
; #pragma unroll
;                 for (int kc = 0; kc < 8; ++kc) { const bf16x8 a0 = *(const LAS bf16x8*)(Ks + 32 * kc), a1 = *(const LAS bf16x8*)(Ks + 32 * KST + 32 * kc);
;                     s0 = MFMA32(a0, qf[kc], s0); s1 = MFMA32(a1, qf[kc], s1); }
;     ...
;                 const unsigned va = vbase + buf * 64 * VST;
;                 u32x2 v[8];
;                 { const bf16x8 pf = pack8(s0, 0); tr8<0, 8 * VST, 64>(va, v);
; #pragma unroll
;                   for (int dt = 0; dt < 4; ++dt) O[dt] = MFMA32(frag2(v[2 * dt], v[2 * dt + 1]), pf, O[dt]); }
;                 { const bf16x8 pf = pack8(s0, 1); tr8<16 * VST, 8 * VST, 64>(va, v);
; #pragma unroll
;                   for (int dt = 0; dt < 4; ++dt) O[dt] = MFMA32(frag2(v[2 * dt], v[2 * dt + 1]), pf, O[dt]); }
;                 { const bf16x8 pf = pack8(s1, 0); tr8<32 * VST, 8 * VST, 64>(va, v);
; #pragma unroll
;                   for (int dt = 0; dt < 4; ++dt) O[dt] = MFMA32(frag2(v[2 * dt], v[2 * dt + 1]), pf, O[dt]); }
;                 { const bf16x8 pf = pack8(s1, 1); tr8<48 * VST, 8 * VST, 64>(va, v);
; #pragma unroll
;                   for (int dt = 0; dt < 4; ++dt) O[dt] = MFMA32(frag2(v[2 * dt], v[2 * dt + 1]), pf, O[dt]); }
.LBB0_747:
	s_cmp_lt_u32 s18, 0x80
	s_cbranch_scc1 .Lmoba_bodyA
	s_cmp_eq_u32 s2, 0
	s_cbranch_scc1 .Lmoba_bodyB
	s_add_i32 s0, s100, 3
	s_and_b32 s0, s0, 3
	s_mov_b32 s45, 0
	s_branch .Lmoba_pvblk
.Lmoba_pvblk:
	s_lshl_b32 s5, s0, 14
	s_add_i32 s5, s5, 0x12000
	s_cmp_eq_u32 s0, 0
	s_cselect_b32 s5, 0xc000, s5
	v_add_u32_e32 v170, s5, v229
	v_xor_b32_e32 v171, 0x40, v170
	v_xor_b32_e32 v172, 0x80, v170
	v_xor_b32_e32 v173, 0xc0, v170
	ds_read_b64_tr_b16 v[66:67], v170 offset:16
	ds_read_b64_tr_b16 v[68:69], v170 offset:2064
	ds_read_b64_tr_b16 v[70:71], v171 offset:16
	ds_read_b64_tr_b16 v[72:73], v171 offset:2064
	ds_read_b64_tr_b16 v[74:75], v172 offset:16
	ds_read_b64_tr_b16 v[76:77], v172 offset:2064
	ds_read_b64_tr_b16 v[78:79], v173 offset:16
	ds_read_b64_tr_b16 v[80:81], v173 offset:2064
	ds_read_b64_tr_b16 v[82:83], v170 offset:4112
	ds_read_b64_tr_b16 v[84:85], v170 offset:6160
	ds_read_b64_tr_b16 v[86:87], v171 offset:4112
	ds_read_b64_tr_b16 v[88:89], v171 offset:6160
	ds_read_b64_tr_b16 v[90:91], v172 offset:4112
	ds_read_b64_tr_b16 v[92:93], v172 offset:6160
	ds_read_b64_tr_b16 v[94:95], v173 offset:4112
	ds_read_b64_tr_b16 v[96:97], v173 offset:6160
	s_waitcnt lgkmcnt(8)
	v_mfma_f32_32x32x16_bf16 v[50:65], v[66:69], v[114:117], v[50:65]
	v_mfma_f32_32x32x16_bf16 v[34:49], v[70:73], v[114:117], v[34:49]
	v_mfma_f32_32x32x16_bf16 v[18:33], v[74:77], v[114:117], v[18:33]
	v_mfma_f32_32x32x16_bf16 v[2:17], v[78:81], v[114:117], v[2:17]
	ds_read_b64_tr_b16 v[66:67], v170 offset:8208
	ds_read_b64_tr_b16 v[68:69], v170 offset:10256
	ds_read_b64_tr_b16 v[70:71], v171 offset:8208
	ds_read_b64_tr_b16 v[72:73], v171 offset:10256
	ds_read_b64_tr_b16 v[74:75], v172 offset:8208
	ds_read_b64_tr_b16 v[76:77], v172 offset:10256
	ds_read_b64_tr_b16 v[78:79], v173 offset:8208
	ds_read_b64_tr_b16 v[80:81], v173 offset:10256
	s_waitcnt lgkmcnt(8)
	v_mfma_f32_32x32x16_bf16 v[50:65], v[82:85], v[118:121], v[50:65]
	v_mfma_f32_32x32x16_bf16 v[34:49], v[86:89], v[118:121], v[34:49]
	v_mfma_f32_32x32x16_bf16 v[18:33], v[90:93], v[118:121], v[18:33]
	v_mfma_f32_32x32x16_bf16 v[2:17], v[94:97], v[118:121], v[2:17]
	ds_read_b64_tr_b16 v[82:83], v170 offset:12304
	ds_read_b64_tr_b16 v[84:85], v170 offset:14352
	ds_read_b64_tr_b16 v[86:87], v171 offset:12304
	ds_read_b64_tr_b16 v[88:89], v171 offset:14352
	ds_read_b64_tr_b16 v[90:91], v172 offset:12304
	ds_read_b64_tr_b16 v[92:93], v172 offset:14352
	ds_read_b64_tr_b16 v[94:95], v173 offset:12304
	ds_read_b64_tr_b16 v[96:97], v173 offset:14352
	s_waitcnt lgkmcnt(8)
	v_mfma_f32_32x32x16_bf16 v[50:65], v[66:69], v[98:101], v[50:65]
	v_mfma_f32_32x32x16_bf16 v[34:49], v[70:73], v[98:101], v[34:49]
	v_mfma_f32_32x32x16_bf16 v[18:33], v[74:77], v[98:101], v[18:33]
	v_mfma_f32_32x32x16_bf16 v[2:17], v[78:81], v[98:101], v[2:17]
	s_waitcnt lgkmcnt(0)
	v_mfma_f32_32x32x16_bf16 v[50:65], v[82:85], v[102:105], v[50:65]
	v_mfma_f32_32x32x16_bf16 v[34:49], v[86:89], v[102:105], v[34:49]
	v_mfma_f32_32x32x16_bf16 v[18:33], v[90:93], v[102:105], v[18:33]
	v_mfma_f32_32x32x16_bf16 v[2:17], v[94:97], v[102:105], v[2:17]
	s_mov_b32 s2, 0
	s_cmp_eq_u32 s45, 0
	s_cbranch_scc1 .Lmoba_bodyB
	s_cmp_eq_u32 s45, 1
	s_cbranch_scc1 .Lmoba_ret1
	s_branch .LBB0_734
.Lmoba_bodyB:
	s_lshl_b32 s0, s19, 8
	s_lshl_b32 s1, s37, 6
	s_add_i32 s1, s1, s0
	s_or_b32 s4, s1, 63
	s_lshl_b32 s0, s101, 14
	v_add_u32_e32 v162, s0, v228
	v_or_b32_e32 v1, s1, v180
	v_sub_u32_e32 v1, v218, v1
	v_xor_b32_e32 v163, 0x20, v162
	v_xor_b32_e32 v164, 0x40, v162
	v_xor_b32_e32 v165, 0x60, v162
	v_xor_b32_e32 v166, 0x80, v162
	v_xor_b32_e32 v167, 0xa0, v162
	v_xor_b32_e32 v168, 0xc0, v162
	v_xor_b32_e32 v169, 0xe0, v162
	s_sub_i32 s0, s6, s4
	s_cmpk_lt_i32 s0, 0x316
	s_cbranch_scc0 .Lmoba_farB
	v_lshl_add_u32 v223, v1, 2, s3
	v_add_u32_e32 v223, 0xffffff14, v223
	ds_read2_b32 v[114:115], v223 offset0:59 offset1:58
	ds_read2_b32 v[98:99], v223 offset0:27 offset1:26
	ds_read2_b32 v[116:117], v223 offset0:57 offset1:56
	ds_read2_b32 v[100:101], v223 offset0:25 offset1:24
	ds_read2_b32 v[118:119], v223 offset0:51 offset1:50
	ds_read2_b32 v[102:103], v223 offset0:19 offset1:18
	ds_read2_b32 v[120:121], v223 offset0:49 offset1:48
	ds_read2_b32 v[104:105], v223 offset0:17 offset1:16
	ds_read2_b32 v[122:123], v223 offset0:43 offset1:42
	ds_read2_b32 v[106:107], v223 offset0:11 offset1:10
	ds_read2_b32 v[124:125], v223 offset0:41 offset1:40
	ds_read2_b32 v[108:109], v223 offset0:9 offset1:8
	ds_read2_b32 v[126:127], v223 offset0:35 offset1:34
	ds_read2_b32 v[110:111], v223 offset0:3 offset1:2
	ds_read2_b32 v[128:129], v223 offset0:33 offset1:32
	ds_read2_b32 v[112:113], v223 offset0:1 offset1:0
	v_mov_b32_e32 v251, 0
	ds_read_b128 v[66:69], v162 offset:16
	ds_read_b128 v[70:73], v162 offset:8208
	ds_read_b128 v[74:77], v163 offset:16
	ds_read_b128 v[78:81], v163 offset:8208
	ds_read_b128 v[82:85], v164 offset:16
	ds_read_b128 v[86:89], v164 offset:8208
	ds_read_b128 v[90:93], v165 offset:16
	ds_read_b128 v[94:97], v165 offset:8208
	s_waitcnt lgkmcnt(7)
	v_mfma_f32_32x32x16_bf16 v[114:129], v[66:69], v[130:133], v[114:129]
	ds_read_b128 v[66:69], v166 offset:16
	s_waitcnt lgkmcnt(7)
	v_mfma_f32_32x32x16_bf16 v[98:113], v[70:73], v[130:133], v[98:113]
	ds_read_b128 v[70:73], v166 offset:8208
	s_branch .Lmoba_scontB
; #define LAS __attribute__((address_space(3)))
; #define MFMA32(a, b, c) __builtin_amdgcn_mfma_f32_32x32x16_bf16((a), (b), (c), 0, 0, 0)
; __device__ __forceinline__ void phase_moba_mfma(const Params& p, LAS unsigned char* lds, unsigned lds_base) {
;     ...
;                 for (int kc = 0; kc < 8; ++kc) { const bf16x8 a0 = *(const LAS bf16x8*)(Ks + 32 * kc), a1 = *(const LAS bf16x8*)(Ks + 32 * KST + 32 * kc);
;                     s0 = MFMA32(a0, qf[kc], s0); s1 = MFMA32(a1, qf[kc], s1); }
;                 const int tq = q0 + i32, kbase = j * 256 + kt * 64;
;                 const bool far = (q0 - (kbase + 63)) >= 790;
;                 const bool diag = own && (kbase + 63 > q0);
;                 const bool lsel = own || ((sel >> j) & 1u);
;                 const int db = tq - kbase - 4 * hh;
;                 if (far) {
; #pragma unroll
;                     for (int r = 0; r < 16; ++r) { s0[r] += c31; s1[r] += c31; }
;                 } else {
;                     const LAS float* bp = (const LAS float*)(lds + OFF_BT) + db;
;                     float b0[16], b1[16];
; #pragma unroll
;                     for (int r = 0; r < 16; ++r) { b0[r] = bp[-(8 * (r >> 2) + (r & 3))]; b1[r] = bp[-(32 + 8 * (r >> 2) + (r & 3))]; }
; #pragma unroll
;                     for (int r = 0; r < 16; ++r) { s0[r] += b0[r]; s1[r] += b1[r]; }
;                 }
;                 if (diag) {
; #pragma unroll
;                     for (int r = 0; r < 16; ++r) { const int d0 = db - (8 * (r >> 2) + (r & 3)); if (d0 < 0) s0[r] = NINF; if (d0 < 32) s1[r] = NINF; }
;                 }
.Lmoba_farB:
	v_mov_b32_e32 v251, v204
	ds_read_b128 v[66:69], v162 offset:16
	ds_read_b128 v[70:73], v162 offset:8208
	ds_read_b128 v[74:77], v163 offset:16
	ds_read_b128 v[78:81], v163 offset:8208
	ds_read_b128 v[82:85], v164 offset:16
	ds_read_b128 v[86:89], v164 offset:8208
	ds_read_b128 v[90:93], v165 offset:16
	ds_read_b128 v[94:97], v165 offset:8208
	s_waitcnt lgkmcnt(7)
	v_mfma_f32_32x32x16_bf16 v[114:129], v[66:69], v[130:133], 0
	ds_read_b128 v[66:69], v166 offset:16
	s_waitcnt lgkmcnt(7)
	v_mfma_f32_32x32x16_bf16 v[98:113], v[70:73], v[130:133], 0
	ds_read_b128 v[70:73], v166 offset:8208
.Lmoba_scontB:
	s_waitcnt lgkmcnt(7)
	v_mfma_f32_32x32x16_bf16 v[114:129], v[74:77], v[134:137], v[114:129]
	ds_read_b128 v[74:77], v167 offset:16
	s_waitcnt lgkmcnt(7)
	v_mfma_f32_32x32x16_bf16 v[98:113], v[78:81], v[134:137], v[98:113]
	ds_read_b128 v[78:81], v167 offset:8208
	s_waitcnt lgkmcnt(7)
	v_mfma_f32_32x32x16_bf16 v[114:129], v[82:85], v[138:141], v[114:129]
	ds_read_b128 v[82:85], v168 offset:16
	s_waitcnt lgkmcnt(7)
	v_mfma_f32_32x32x16_bf16 v[98:113], v[86:89], v[138:141], v[98:113]
	ds_read_b128 v[86:89], v168 offset:8208
	s_waitcnt lgkmcnt(7)
	v_mfma_f32_32x32x16_bf16 v[114:129], v[90:93], v[142:145], v[114:129]
	ds_read_b128 v[90:93], v169 offset:16
	s_waitcnt lgkmcnt(7)
	v_mfma_f32_32x32x16_bf16 v[98:113], v[94:97], v[142:145], v[98:113]
	ds_read_b128 v[94:97], v169 offset:8208
	s_waitcnt lgkmcnt(7)
	v_mfma_f32_32x32x16_bf16 v[114:129], v[66:69], v[146:149], v[114:129]
	s_waitcnt lgkmcnt(6)
	v_mfma_f32_32x32x16_bf16 v[98:113], v[70:73], v[146:149], v[98:113]
	s_waitcnt lgkmcnt(5)
	v_mfma_f32_32x32x16_bf16 v[114:129], v[74:77], v[150:153], v[114:129]
	s_waitcnt lgkmcnt(4)
	v_mfma_f32_32x32x16_bf16 v[98:113], v[78:81], v[150:153], v[98:113]
	s_waitcnt lgkmcnt(3)
	v_mfma_f32_32x32x16_bf16 v[114:129], v[82:85], v[154:157], v[114:129]
	s_waitcnt lgkmcnt(2)
	v_mfma_f32_32x32x16_bf16 v[98:113], v[86:89], v[154:157], v[98:113]
	s_waitcnt lgkmcnt(1)
	v_mfma_f32_32x32x16_bf16 v[114:129], v[90:93], v[158:161], v[114:129]
	s_waitcnt lgkmcnt(0)
	v_mfma_f32_32x32x16_bf16 v[98:113], v[94:97], v[158:161], v[98:113]
	s_nop 7
	s_cmp_ge_i32 s6, s4
	s_cselect_b64 s[0:1], -1, 0
	s_xor_b64 s[4:5], s[16:17], -1
	s_or_b64 s[0:1], s[4:5], s[0:1]
	s_and_b64 vcc, exec, s[0:1]
	s_cbranch_vccnz .Lmoba_nodiagB
	v_cmp_gt_i32_e64 s[4:5], 26, v1
	v_cmp_gt_i32_e32 vcc, 27, v1
	v_cmp_gt_i32_e64 s[96:97], 25, v1
	v_cmp_gt_i32_e64 s[94:95], 24, v1
	v_cndmask_b32_e32 v129, v129, v217, vcc
	s_and_b64 vcc, vcc, s[4:5]
	v_cndmask_b32_e32 v128, v128, v217, vcc
	s_and_b64 vcc, vcc, s[96:97]
	v_cmp_gt_i32_e64 s[92:93], 19, v1
	v_cndmask_b32_e32 v127, v127, v217, vcc
	s_and_b64 vcc, vcc, s[94:95]
	v_cmp_gt_i32_e64 s[90:91], 18, v1
	v_cndmask_b32_e32 v126, v126, v217, vcc
	s_and_b64 vcc, vcc, s[92:93]
	v_cmp_gt_i32_e64 s[88:89], 17, v1
	v_cndmask_b32_e32 v125, v125, v217, vcc
	s_and_b64 vcc, vcc, s[90:91]
	v_cmp_gt_i32_e64 s[86:87], 16, v1
	v_cndmask_b32_e32 v124, v124, v217, vcc
	s_and_b64 vcc, vcc, s[88:89]
	v_cmp_gt_i32_e64 s[84:85], 11, v1
	v_cndmask_b32_e32 v123, v123, v217, vcc
	s_and_b64 vcc, vcc, s[86:87]
	v_cmp_gt_i32_e64 s[82:83], 10, v1
	v_cndmask_b32_e32 v122, v122, v217, vcc
	s_and_b64 vcc, vcc, s[84:85]
	v_cmp_gt_i32_e64 s[80:81], 9, v1
	v_cndmask_b32_e32 v121, v121, v217, vcc
	s_and_b64 vcc, vcc, s[82:83]
	v_cmp_gt_i32_e64 s[78:79], 8, v1
	v_cndmask_b32_e32 v120, v120, v217, vcc
	s_and_b64 vcc, vcc, s[80:81]
	v_cmp_gt_i32_e64 s[76:77], 3, v1
	v_cndmask_b32_e32 v119, v119, v217, vcc
	s_and_b64 vcc, vcc, s[78:79]
	v_cmp_gt_i32_e64 s[74:75], 2, v1
	v_cndmask_b32_e32 v118, v118, v217, vcc
	s_and_b64 vcc, vcc, s[76:77]
	v_cmp_gt_i32_e64 s[72:73], 1, v1
	v_cndmask_b32_e32 v117, v117, v217, vcc
	s_and_b64 vcc, vcc, s[74:75]
	v_cmp_gt_i32_e64 s[66:67], 0, v1
	v_cndmask_b32_e32 v116, v116, v217, vcc
	s_and_b64 vcc, vcc, s[72:73]
	v_cndmask_b32_e32 v115, v115, v217, vcc
	s_and_b64 vcc, vcc, s[66:67]
	v_cmp_gt_i32_e64 s[64:65], 58, v1
	v_cndmask_b32_e32 v114, v114, v217, vcc
	v_cmp_gt_i32_e32 vcc, 59, v1
	v_cmp_gt_i32_e64 s[62:63], 57, v1
	v_cmp_gt_i32_e64 s[60:61], 56, v1
	v_cndmask_b32_e32 v113, v113, v217, vcc
	s_and_b64 vcc, vcc, s[64:65]
	v_cndmask_b32_e32 v112, v112, v217, vcc
	s_and_b64 vcc, vcc, s[62:63]
	v_cmp_gt_i32_e64 s[58:59], 51, v1
	v_cndmask_b32_e32 v111, v111, v217, vcc
	s_and_b64 vcc, vcc, s[60:61]
	v_cmp_gt_i32_e64 s[56:57], 50, v1
	v_cndmask_b32_e32 v110, v110, v217, vcc
	s_and_b64 vcc, vcc, s[58:59]
	v_cmp_gt_i32_e64 s[54:55], 49, v1
	v_cndmask_b32_e32 v109, v109, v217, vcc
	s_and_b64 vcc, vcc, s[56:57]
	v_cmp_gt_i32_e64 s[52:53], 48, v1
	v_cndmask_b32_e32 v108, v108, v217, vcc
	s_and_b64 vcc, vcc, s[54:55]
	v_cmp_gt_i32_e64 s[50:51], 43, v1
	v_cndmask_b32_e32 v107, v107, v217, vcc
	s_and_b64 vcc, vcc, s[52:53]
	v_cmp_gt_i32_e64 s[48:49], 42, v1
	v_cndmask_b32_e32 v106, v106, v217, vcc
	s_and_b64 vcc, vcc, s[50:51]
	v_cmp_gt_i32_e64 s[46:47], 41, v1
	v_cndmask_b32_e32 v105, v105, v217, vcc
	s_and_b64 vcc, vcc, s[48:49]
	v_cmp_gt_i32_e64 s[44:45], 40, v1
	v_cndmask_b32_e32 v104, v104, v217, vcc
	s_and_b64 vcc, vcc, s[46:47]
	v_cmp_gt_i32_e64 s[42:43], 35, v1
	v_cndmask_b32_e32 v103, v103, v217, vcc
	s_and_b64 vcc, vcc, s[44:45]
	v_cmp_gt_i32_e64 s[40:41], 34, v1
	v_cndmask_b32_e32 v102, v102, v217, vcc
	s_and_b64 vcc, vcc, s[42:43]
	v_cmp_gt_i32_e64 s[0:1], 33, v1
	v_cndmask_b32_e32 v101, v101, v217, vcc
	s_and_b64 vcc, vcc, s[40:41]
	v_cmp_gt_i32_e64 s[70:71], 32, v1
	v_cndmask_b32_e32 v100, v100, v217, vcc
	s_and_b64 vcc, vcc, s[0:1]
	v_cndmask_b32_e32 v99, v99, v217, vcc
	s_and_b64 vcc, vcc, s[70:71]
	v_cndmask_b32_e32 v98, v98, v217, vcc

; #define LAS __attribute__((address_space(3)))
; #define MFMA32(a, b, c) __builtin_amdgcn_mfma_f32_32x32x16_bf16((a), (b), (c), 0, 0, 0)
; __device__ __forceinline__ void phase_moba_mfma(const Params& p, LAS unsigned char* lds, unsigned lds_base) {
;     ...
;             if (need) {
;                 const LAS unsigned char* Ks = lds + OFF_K + buf * 64 * KST + i32 * KST + 16 * hh;
;                 f32x16 s0, s1;
; #pragma unroll
;                 for (int r = 0; r < 16; ++r) { s0[r] = 0.f; s1[r] = 0.f; }
; #pragma unroll
;                 for (int kc = 0; kc < 8; ++kc) { const bf16x8 a0 = *(const LAS bf16x8*)(Ks + 32 * kc), a1 = *(const LAS bf16x8*)(Ks + 32 * KST + 32 * kc);
;                     s0 = MFMA32(a0, qf[kc], s0); s1 = MFMA32(a1, qf[kc], s1); }
;                 const int tq = q0 + i32, kbase = j * 256 + kt * 64;
;                 const bool far = (q0 - (kbase + 63)) >= 790;
;                 const bool diag = own && (kbase + 63 > q0);
;     ...
;                 const float mnew = fmaxf(m, mx);
;                 const float alpha = __builtin_amdgcn_exp2f(m - mnew);
;                 float ps = 0.f;
; #pragma unroll
;                 for (int r = 0; r < 16; ++r) { s0[r] = __builtin_amdgcn_exp2f(s0[r] - mnew); s1[r] = __builtin_amdgcn_exp2f(s1[r] - mnew); ps += s0[r] + s1[r]; }
;                 l = l * alpha + ps; m = mnew;
.Lmoba_norsB:
	v_cndmask_b32_e64 v246, v248, v1, s[0:1]
	v_sub_f32_e32 v246, v246, v251
	v_sub_f32_e32 v114, v114, v246
	v_sub_f32_e32 v115, v115, v246
	v_sub_f32_e32 v116, v116, v246
	v_sub_f32_e32 v117, v117, v246
	v_sub_f32_e32 v118, v118, v246
	v_sub_f32_e32 v119, v119, v246
	v_sub_f32_e32 v120, v120, v246
	v_sub_f32_e32 v121, v121, v246
	v_exp_f32_e32 v114, v114
	v_exp_f32_e32 v115, v115
	v_exp_f32_e32 v116, v116
	v_exp_f32_e32 v117, v117
	v_exp_f32_e32 v118, v118
	v_exp_f32_e32 v119, v119
	v_exp_f32_e32 v120, v120
	v_exp_f32_e32 v121, v121
	v_add_f32_e32 v240, v114, v115
	v_add_f32_e32 v240, v240, v116
	v_add_f32_e32 v241, v241, v117
	v_add_f32_e32 v240, v240, v118
	v_add_f32_e32 v241, v241, v119
	v_add_f32_e32 v240, v240, v120
	v_add_f32_e32 v241, v241, v121
	v_cvt_pk_bf16_f32 v114, v114, v115
	v_cvt_pk_bf16_f32 v115, v116, v117
	v_cvt_pk_bf16_f32 v116, v118, v119
	v_cvt_pk_bf16_f32 v117, v120, v121
	v_sub_f32_e32 v122, v122, v246
	v_sub_f32_e32 v123, v123, v246
	v_sub_f32_e32 v124, v124, v246
	v_sub_f32_e32 v125, v125, v246
	v_sub_f32_e32 v126, v126, v246
	v_sub_f32_e32 v127, v127, v246
	v_sub_f32_e32 v128, v128, v246
	v_sub_f32_e32 v129, v129, v246
	v_exp_f32_e32 v122, v122
	v_exp_f32_e32 v123, v123
	v_exp_f32_e32 v124, v124
	v_exp_f32_e32 v125, v125
	v_exp_f32_e32 v126, v126
	v_exp_f32_e32 v127, v127
	v_exp_f32_e32 v128, v128
	v_exp_f32_e32 v129, v129
	v_add_f32_e32 v240, v240, v122
	v_add_f32_e32 v241, v241, v123
	v_add_f32_e32 v240, v240, v124
	v_add_f32_e32 v241, v241, v125
	v_add_f32_e32 v240, v240, v126
	v_add_f32_e32 v241, v241, v127
	v_add_f32_e32 v240, v240, v128
	v_add_f32_e32 v241, v241, v129
	v_cvt_pk_bf16_f32 v118, v122, v123
	v_cvt_pk_bf16_f32 v119, v124, v125
	v_cvt_pk_bf16_f32 v120, v126, v127
	v_cvt_pk_bf16_f32 v121, v128, v129
	v_sub_f32_e32 v98, v98, v246
	v_sub_f32_e32 v99, v99, v246
	v_sub_f32_e32 v100, v100, v246
	v_sub_f32_e32 v101, v101, v246
	v_sub_f32_e32 v102, v102, v246
	v_sub_f32_e32 v103, v103, v246
	v_sub_f32_e32 v104, v104, v246
	v_sub_f32_e32 v105, v105, v246
	v_exp_f32_e32 v98, v98
	v_exp_f32_e32 v99, v99
	v_exp_f32_e32 v100, v100
	v_exp_f32_e32 v101, v101
	v_exp_f32_e32 v102, v102
	v_exp_f32_e32 v103, v103
	v_exp_f32_e32 v104, v104
	v_exp_f32_e32 v105, v105
	v_add_f32_e32 v240, v240, v98
	v_add_f32_e32 v241, v241, v99
	v_add_f32_e32 v240, v240, v100
	v_add_f32_e32 v241, v241, v101
	v_add_f32_e32 v240, v240, v102
	v_add_f32_e32 v241, v241, v103
	v_add_f32_e32 v240, v240, v104
	v_add_f32_e32 v241, v241, v105
	v_cvt_pk_bf16_f32 v98, v98, v99
	v_cvt_pk_bf16_f32 v99, v100, v101
	v_cvt_pk_bf16_f32 v100, v102, v103
	v_cvt_pk_bf16_f32 v101, v104, v105
	v_sub_f32_e32 v106, v106, v246
	v_sub_f32_e32 v107, v107, v246
	v_sub_f32_e32 v108, v108, v246
	v_sub_f32_e32 v109, v109, v246
	v_sub_f32_e32 v110, v110, v246
	v_sub_f32_e32 v111, v111, v246
	v_sub_f32_e32 v112, v112, v246
	v_sub_f32_e32 v113, v113, v246
	v_exp_f32_e32 v106, v106
	v_exp_f32_e32 v107, v107
	v_exp_f32_e32 v108, v108
	v_exp_f32_e32 v109, v109
	v_exp_f32_e32 v110, v110
	v_exp_f32_e32 v111, v111
	v_exp_f32_e32 v112, v112
	v_exp_f32_e32 v113, v113
	v_add_f32_e32 v240, v240, v106
	v_add_f32_e32 v241, v241, v107
	v_add_f32_e32 v240, v240, v108
	v_add_f32_e32 v241, v241, v109
	v_add_f32_e32 v240, v240, v110
	v_add_f32_e32 v241, v241, v111
	v_add_f32_e32 v240, v240, v112
	v_add_f32_e32 v241, v241, v113
	v_cvt_pk_bf16_f32 v102, v106, v107
	v_cvt_pk_bf16_f32 v103, v108, v109
	v_cvt_pk_bf16_f32 v104, v110, v111
	v_cvt_pk_bf16_f32 v105, v112, v113
	v_add_f32_e32 v240, v240, v241
	v_add_f32_e32 v219, v219, v240
	s_mov_b32 s2, 1
	s_branch .Lmoba_tail
.Lmoba_bodyA:
	s_lshl_b32 s0, s19, 8
	s_lshl_b32 s1, s37, 6
	s_add_i32 s1, s1, s0
	s_or_b32 s4, s1, 63
	s_lshl_b32 s0, s101, 14
	v_add_u32_e32 v162, s0, v228
	v_or_b32_e32 v1, s1, v180
	v_sub_u32_e32 v1, v218, v1
	v_xor_b32_e32 v163, 0x20, v162
	v_xor_b32_e32 v164, 0x40, v162
	v_xor_b32_e32 v165, 0x60, v162
	v_xor_b32_e32 v166, 0x80, v162
	v_xor_b32_e32 v167, 0xa0, v162
	v_xor_b32_e32 v168, 0xc0, v162
	v_xor_b32_e32 v169, 0xe0, v162
	s_lshl_b32 s5, s100, 14
	s_add_i32 s5, s5, 0x12000
	s_cmp_eq_u32 s100, 0
	s_cselect_b32 s5, 0xc000, s5
	v_add_u32_e32 v170, s5, v229
	v_xor_b32_e32 v171, 0x40, v170
	v_xor_b32_e32 v172, 0x80, v170
	v_xor_b32_e32 v173, 0xc0, v170
	s_sub_i32 s0, s6, s4
	s_cmpk_lt_i32 s0, 0x316
	s_cbranch_scc0 .Lmoba_farA
	v_lshl_add_u32 v223, v1, 2, s3
	v_add_u32_e32 v223, 0xffffff14, v223
	ds_read2_b32 v[114:115], v223 offset0:59 offset1:58
	ds_read2_b32 v[98:99], v223 offset0:27 offset1:26
	ds_read2_b32 v[116:117], v223 offset0:57 offset1:56
	ds_read2_b32 v[100:101], v223 offset0:25 offset1:24
	ds_read2_b32 v[118:119], v223 offset0:51 offset1:50
	ds_read2_b32 v[102:103], v223 offset0:19 offset1:18
	ds_read2_b32 v[120:121], v223 offset0:49 offset1:48
	ds_read2_b32 v[104:105], v223 offset0:17 offset1:16
	ds_read2_b32 v[122:123], v223 offset0:43 offset1:42
	ds_read2_b32 v[106:107], v223 offset0:11 offset1:10
	ds_read2_b32 v[124:125], v223 offset0:41 offset1:40
	ds_read2_b32 v[108:109], v223 offset0:9 offset1:8
	ds_read2_b32 v[126:127], v223 offset0:35 offset1:34
	ds_read2_b32 v[110:111], v223 offset0:3 offset1:2
	ds_read2_b32 v[128:129], v223 offset0:33 offset1:32
	ds_read2_b32 v[112:113], v223 offset0:1 offset1:0
	v_mov_b32_e32 v251, 0
	ds_read_b128 v[66:69], v162 offset:16
	ds_read_b128 v[70:73], v162 offset:8208
	ds_read_b128 v[74:77], v163 offset:16
	ds_read_b128 v[78:81], v163 offset:8208
	ds_read_b128 v[82:85], v164 offset:16
	ds_read_b128 v[86:89], v164 offset:8208
	ds_read_b128 v[90:93], v165 offset:16
	ds_read_b128 v[94:97], v165 offset:8208
	s_waitcnt lgkmcnt(7)
	v_mfma_f32_32x32x16_bf16 v[114:129], v[66:69], v[130:133], v[114:129]
	ds_read_b128 v[66:69], v166 offset:16
	s_waitcnt lgkmcnt(7)
	v_mfma_f32_32x32x16_bf16 v[98:113], v[70:73], v[130:133], v[98:113]
	ds_read_b128 v[70:73], v166 offset:8208
	s_branch .Lmoba_scontA

; #define LAS __attribute__((address_space(3)))
; #define MFMA32(a, b, c) __builtin_amdgcn_mfma_f32_32x32x16_bf16((a), (b), (c), 0, 0, 0)
; __device__ __forceinline__ void phase_moba_mfma(const Params& p, LAS unsigned char* lds, unsigned lds_base) {
;     ...
;                 for (int kc = 0; kc < 8; ++kc) { const bf16x8 a0 = *(const LAS bf16x8*)(Ks + 32 * kc), a1 = *(const LAS bf16x8*)(Ks + 32 * KST + 32 * kc);
;                     s0 = MFMA32(a0, qf[kc], s0); s1 = MFMA32(a1, qf[kc], s1); }
;                 const int tq = q0 + i32, kbase = j * 256 + kt * 64;
;                 const bool far = (q0 - (kbase + 63)) >= 790;
;                 const bool diag = own && (kbase + 63 > q0);
;                 const bool lsel = own || ((sel >> j) & 1u);
;                 const int db = tq - kbase - 4 * hh;
;                 if (far) {
; #pragma unroll
;                     for (int r = 0; r < 16; ++r) { s0[r] += c31; s1[r] += c31; }
;                 } else {
;                     const LAS float* bp = (const LAS float*)(lds + OFF_BT) + db;
;                     float b0[16], b1[16];
; #pragma unroll
;                     for (int r = 0; r < 16; ++r) { b0[r] = bp[-(8 * (r >> 2) + (r & 3))]; b1[r] = bp[-(32 + 8 * (r >> 2) + (r & 3))]; }
; #pragma unroll
;                     for (int r = 0; r < 16; ++r) { s0[r] += b0[r]; s1[r] += b1[r]; }
;                 }
;                 if (diag) {
; #pragma unroll
;                     for (int r = 0; r < 16; ++r) { const int d0 = db - (8 * (r >> 2) + (r & 3)); if (d0 < 0) s0[r] = NINF; if (d0 < 32) s1[r] = NINF; }
.Lmoba_scontA:
	s_waitcnt lgkmcnt(7)
	v_mfma_f32_32x32x16_bf16 v[114:129], v[74:77], v[134:137], v[114:129]
	ds_read_b128 v[74:77], v167 offset:16
	s_waitcnt lgkmcnt(7)
	v_mfma_f32_32x32x16_bf16 v[98:113], v[78:81], v[134:137], v[98:113]
	ds_read_b128 v[78:81], v167 offset:8208
	s_waitcnt lgkmcnt(7)
	v_mfma_f32_32x32x16_bf16 v[114:129], v[82:85], v[138:141], v[114:129]
	ds_read_b128 v[82:85], v168 offset:16
	s_waitcnt lgkmcnt(7)
	v_mfma_f32_32x32x16_bf16 v[98:113], v[86:89], v[138:141], v[98:113]
	ds_read_b128 v[86:89], v168 offset:8208
	s_waitcnt lgkmcnt(7)
	v_mfma_f32_32x32x16_bf16 v[114:129], v[90:93], v[142:145], v[114:129]
	ds_read_b128 v[90:93], v169 offset:16
	s_waitcnt lgkmcnt(7)
	v_mfma_f32_32x32x16_bf16 v[98:113], v[94:97], v[142:145], v[98:113]
	ds_read_b128 v[94:97], v169 offset:8208
	s_waitcnt lgkmcnt(7)
	v_mfma_f32_32x32x16_bf16 v[114:129], v[66:69], v[146:149], v[114:129]
	s_waitcnt lgkmcnt(6)
	v_mfma_f32_32x32x16_bf16 v[98:113], v[70:73], v[146:149], v[98:113]
	s_waitcnt lgkmcnt(5)
	v_mfma_f32_32x32x16_bf16 v[114:129], v[74:77], v[150:153], v[114:129]
	s_waitcnt lgkmcnt(4)
	v_mfma_f32_32x32x16_bf16 v[98:113], v[78:81], v[150:153], v[98:113]
	s_waitcnt lgkmcnt(3)
	v_mfma_f32_32x32x16_bf16 v[114:129], v[82:85], v[154:157], v[114:129]
	s_waitcnt lgkmcnt(2)
	v_mfma_f32_32x32x16_bf16 v[98:113], v[86:89], v[154:157], v[98:113]
	s_waitcnt lgkmcnt(1)
	v_mfma_f32_32x32x16_bf16 v[114:129], v[90:93], v[158:161], v[114:129]
	s_waitcnt lgkmcnt(0)
	v_mfma_f32_32x32x16_bf16 v[98:113], v[94:97], v[158:161], v[98:113]
	ds_read_b64_tr_b16 v[66:67], v170 offset:16
	ds_read_b64_tr_b16 v[68:69], v170 offset:2064
	ds_read_b64_tr_b16 v[70:71], v171 offset:16
	ds_read_b64_tr_b16 v[72:73], v171 offset:2064
	ds_read_b64_tr_b16 v[74:75], v172 offset:16
	ds_read_b64_tr_b16 v[76:77], v172 offset:2064
	ds_read_b64_tr_b16 v[78:79], v173 offset:16
	ds_read_b64_tr_b16 v[80:81], v173 offset:2064
	ds_read_b64_tr_b16 v[82:83], v170 offset:4112
	ds_read_b64_tr_b16 v[84:85], v170 offset:6160
	ds_read_b64_tr_b16 v[86:87], v171 offset:4112
	ds_read_b64_tr_b16 v[88:89], v171 offset:6160
	ds_read_b64_tr_b16 v[90:91], v172 offset:4112
	ds_read_b64_tr_b16 v[92:93], v172 offset:6160
	ds_read_b64_tr_b16 v[94:95], v173 offset:4112
	ds_read_b64_tr_b16 v[96:97], v173 offset:6160
	s_cmp_ge_i32 s6, s4
	s_cselect_b64 s[0:1], -1, 0
	s_xor_b64 s[4:5], s[16:17], -1
	s_or_b64 s[0:1], s[4:5], s[0:1]
	s_and_b64 vcc, exec, s[0:1]
	s_cbranch_vccnz .Lmoba_nodiagA
	v_cmp_gt_i32_e64 s[4:5], 26, v1
	v_cmp_gt_i32_e32 vcc, 27, v1
	v_cmp_gt_i32_e64 s[96:97], 25, v1
	v_cmp_gt_i32_e64 s[94:95], 24, v1
	v_cndmask_b32_e32 v129, v129, v217, vcc
	s_and_b64 vcc, vcc, s[4:5]
	v_cndmask_b32_e32 v128, v128, v217, vcc
	s_and_b64 vcc, vcc, s[96:97]
	v_cmp_gt_i32_e64 s[92:93], 19, v1
	v_cndmask_b32_e32 v127, v127, v217, vcc
	s_and_b64 vcc, vcc, s[94:95]
	v_cmp_gt_i32_e64 s[90:91], 18, v1
	v_cndmask_b32_e32 v126, v126, v217, vcc
	s_and_b64 vcc, vcc, s[92:93]
	v_cmp_gt_i32_e64 s[88:89], 17, v1
	v_cndmask_b32_e32 v125, v125, v217, vcc
	s_and_b64 vcc, vcc, s[90:91]
	v_cmp_gt_i32_e64 s[86:87], 16, v1
	v_cndmask_b32_e32 v124, v124, v217, vcc
	s_and_b64 vcc, vcc, s[88:89]
	v_cmp_gt_i32_e64 s[84:85], 11, v1
	v_cndmask_b32_e32 v123, v123, v217, vcc
	s_and_b64 vcc, vcc, s[86:87]
	v_cmp_gt_i32_e64 s[82:83], 10, v1
	v_cndmask_b32_e32 v122, v122, v217, vcc
	s_and_b64 vcc, vcc, s[84:85]
	v_cmp_gt_i32_e64 s[80:81], 9, v1
	v_cndmask_b32_e32 v121, v121, v217, vcc
	s_and_b64 vcc, vcc, s[82:83]
	v_cmp_gt_i32_e64 s[78:79], 8, v1
	v_cndmask_b32_e32 v120, v120, v217, vcc
	s_and_b64 vcc, vcc, s[80:81]
	v_cmp_gt_i32_e64 s[76:77], 3, v1
	v_cndmask_b32_e32 v119, v119, v217, vcc
	s_and_b64 vcc, vcc, s[78:79]
	v_cmp_gt_i32_e64 s[74:75], 2, v1
	v_cndmask_b32_e32 v118, v118, v217, vcc
	s_and_b64 vcc, vcc, s[76:77]
	v_cmp_gt_i32_e64 s[72:73], 1, v1
	v_cndmask_b32_e32 v117, v117, v217, vcc
	s_and_b64 vcc, vcc, s[74:75]
	v_cmp_gt_i32_e64 s[66:67], 0, v1
	v_cndmask_b32_e32 v116, v116, v217, vcc
	s_and_b64 vcc, vcc, s[72:73]
	v_cndmask_b32_e32 v115, v115, v217, vcc
	s_and_b64 vcc, vcc, s[66:67]
	v_cmp_gt_i32_e64 s[64:65], 58, v1
	v_cndmask_b32_e32 v114, v114, v217, vcc
	v_cmp_gt_i32_e32 vcc, 59, v1
	v_cmp_gt_i32_e64 s[62:63], 57, v1
	v_cmp_gt_i32_e64 s[60:61], 56, v1
	v_cndmask_b32_e32 v113, v113, v217, vcc
	s_and_b64 vcc, vcc, s[64:65]
	v_cndmask_b32_e32 v112, v112, v217, vcc
	s_and_b64 vcc, vcc, s[62:63]
	v_cmp_gt_i32_e64 s[58:59], 51, v1
	v_cndmask_b32_e32 v111, v111, v217, vcc
	s_and_b64 vcc, vcc, s[60:61]
	v_cmp_gt_i32_e64 s[56:57], 50, v1
	v_cndmask_b32_e32 v110, v110, v217, vcc
	s_and_b64 vcc, vcc, s[58:59]
	v_cmp_gt_i32_e64 s[54:55], 49, v1
	v_cndmask_b32_e32 v109, v109, v217, vcc
	s_and_b64 vcc, vcc, s[56:57]
	v_cmp_gt_i32_e64 s[52:53], 48, v1
	v_cndmask_b32_e32 v108, v108, v217, vcc
	s_and_b64 vcc, vcc, s[54:55]
	v_cmp_gt_i32_e64 s[50:51], 43, v1
	v_cndmask_b32_e32 v107, v107, v217, vcc
	s_and_b64 vcc, vcc, s[52:53]
	v_cmp_gt_i32_e64 s[48:49], 42, v1
	v_cndmask_b32_e32 v106, v106, v217, vcc
	s_and_b64 vcc, vcc, s[50:51]
	v_cmp_gt_i32_e64 s[46:47], 41, v1
	v_cndmask_b32_e32 v105, v105, v217, vcc
	s_and_b64 vcc, vcc, s[48:49]
	v_cmp_gt_i32_e64 s[44:45], 40, v1
	v_cndmask_b32_e32 v104, v104, v217, vcc
	s_and_b64 vcc, vcc, s[46:47]
	v_cmp_gt_i32_e64 s[42:43], 35, v1
	v_cndmask_b32_e32 v103, v103, v217, vcc
	s_and_b64 vcc, vcc, s[44:45]
	v_cmp_gt_i32_e64 s[40:41], 34, v1
	v_cndmask_b32_e32 v102, v102, v217, vcc
	s_and_b64 vcc, vcc, s[42:43]
	v_cmp_gt_i32_e64 s[0:1], 33, v1
	v_cndmask_b32_e32 v101, v101, v217, vcc
	s_and_b64 vcc, vcc, s[40:41]
	v_cmp_gt_i32_e64 s[70:71], 32, v1
	v_cndmask_b32_e32 v100, v100, v217, vcc
	s_and_b64 vcc, vcc, s[0:1]
	v_cndmask_b32_e32 v99, v99, v217, vcc
	s_and_b64 vcc, vcc, s[70:71]
	v_cndmask_b32_e32 v98, v98, v217, vcc

; #define MFMA32(a, b, c) __builtin_amdgcn_mfma_f32_32x32x16_bf16((a), (b), (c), 0, 0, 0)
; __device__ __forceinline__ void phase_moba_mfma(const Params& p, LAS unsigned char* lds, unsigned lds_base) {
;     ...
;                 const float mnew = fmaxf(m, mx);
;                 const float alpha = __builtin_amdgcn_exp2f(m - mnew);
;                 float ps = 0.f;
; #pragma unroll
;                 for (int r = 0; r < 16; ++r) { s0[r] = __builtin_amdgcn_exp2f(s0[r] - mnew); s1[r] = __builtin_amdgcn_exp2f(s1[r] - mnew); ps += s0[r] + s1[r]; }
;                 l = l * alpha + ps; m = mnew;
;                 if (__ballot(alpha != 1.0f) != 0ull) {
; #pragma unroll
;                     for (int dt = 0; dt < 4; ++dt)
; #pragma unroll
;                         for (int r = 0; r < 16; ++r) O[dt][r] *= alpha;
;                 }
;                 const unsigned va = vbase + buf * 64 * VST;
;                 u32x2 v[8];
;                 { const bf16x8 pf = pack8(s0, 0); tr8<0, 8 * VST, 64>(va, v);
; #pragma unroll
;                   for (int dt = 0; dt < 4; ++dt) O[dt] = MFMA32(frag2(v[2 * dt], v[2 * dt + 1]), pf, O[dt]); }
;                 { const bf16x8 pf = pack8(s0, 1); tr8<16 * VST, 8 * VST, 64>(va, v);
; #pragma unroll
;                   for (int dt = 0; dt < 4; ++dt) O[dt] = MFMA32(frag2(v[2 * dt], v[2 * dt + 1]), pf, O[dt]); }
;                 { const bf16x8 pf = pack8(s1, 0); tr8<32 * VST, 8 * VST, 64>(va, v);
; #pragma unroll
;                   for (int dt = 0; dt < 4; ++dt) O[dt] = MFMA32(frag2(v[2 * dt], v[2 * dt + 1]), pf, O[dt]); }
;                 { const bf16x8 pf = pack8(s1, 1); tr8<48 * VST, 8 * VST, 64>(va, v);
; #pragma unroll
;                   for (int dt = 0; dt < 4; ++dt) O[dt] = MFMA32(frag2(v[2 * dt], v[2 * dt + 1]), pf, O[dt]); }
.Lmoba_norsA:
	v_cndmask_b32_e64 v246, v248, v1, s[0:1]
	v_sub_f32_e32 v246, v246, v251
	v_sub_f32_e32 v114, v114, v246
	v_sub_f32_e32 v115, v115, v246
	v_sub_f32_e32 v116, v116, v246
	v_sub_f32_e32 v117, v117, v246
	v_sub_f32_e32 v118, v118, v246
	v_sub_f32_e32 v119, v119, v246
	v_sub_f32_e32 v120, v120, v246
	v_sub_f32_e32 v121, v121, v246
	v_exp_f32_e32 v114, v114
	v_exp_f32_e32 v115, v115
	v_exp_f32_e32 v116, v116
	v_exp_f32_e32 v117, v117
	v_exp_f32_e32 v118, v118
	v_exp_f32_e32 v119, v119
	v_exp_f32_e32 v120, v120
	v_exp_f32_e32 v121, v121
	v_add_f32_e32 v240, v114, v115
	v_add_f32_e32 v240, v240, v116
	v_add_f32_e32 v241, v241, v117
	v_add_f32_e32 v240, v240, v118
	v_add_f32_e32 v241, v241, v119
	v_add_f32_e32 v240, v240, v120
	v_add_f32_e32 v241, v241, v121
	v_cvt_pk_bf16_f32 v114, v114, v115
	v_cvt_pk_bf16_f32 v115, v116, v117
	v_cvt_pk_bf16_f32 v116, v118, v119
	v_cvt_pk_bf16_f32 v117, v120, v121
	v_sub_f32_e32 v122, v122, v246
	v_sub_f32_e32 v123, v123, v246
	s_waitcnt lgkmcnt(0)
	v_mfma_f32_32x32x16_bf16 v[50:65], v[66:69], v[114:117], v[50:65]
	v_mfma_f32_32x32x16_bf16 v[34:49], v[70:73], v[114:117], v[34:49]
	v_mfma_f32_32x32x16_bf16 v[18:33], v[74:77], v[114:117], v[18:33]
	v_mfma_f32_32x32x16_bf16 v[2:17], v[78:81], v[114:117], v[2:17]
	ds_read_b64_tr_b16 v[66:67], v170 offset:8208
	ds_read_b64_tr_b16 v[68:69], v170 offset:10256
	ds_read_b64_tr_b16 v[70:71], v171 offset:8208
	ds_read_b64_tr_b16 v[72:73], v171 offset:10256
	ds_read_b64_tr_b16 v[74:75], v172 offset:8208
	ds_read_b64_tr_b16 v[76:77], v172 offset:10256
	ds_read_b64_tr_b16 v[78:79], v173 offset:8208
	ds_read_b64_tr_b16 v[80:81], v173 offset:10256
	v_sub_f32_e32 v124, v124, v246
	v_sub_f32_e32 v125, v125, v246
	v_sub_f32_e32 v126, v126, v246
	v_sub_f32_e32 v127, v127, v246
	v_sub_f32_e32 v128, v128, v246
	v_sub_f32_e32 v129, v129, v246
	v_exp_f32_e32 v122, v122
	v_exp_f32_e32 v123, v123
	v_exp_f32_e32 v124, v124
	v_exp_f32_e32 v125, v125
	v_exp_f32_e32 v126, v126
	v_exp_f32_e32 v127, v127
	v_exp_f32_e32 v128, v128
	v_exp_f32_e32 v129, v129
	v_add_f32_e32 v240, v240, v122
	v_add_f32_e32 v241, v241, v123
	v_add_f32_e32 v240, v240, v124
	v_add_f32_e32 v241, v241, v125
	v_add_f32_e32 v240, v240, v126
	v_add_f32_e32 v241, v241, v127
	v_add_f32_e32 v240, v240, v128
	v_add_f32_e32 v241, v241, v129
	v_cvt_pk_bf16_f32 v118, v122, v123
	v_cvt_pk_bf16_f32 v119, v124, v125
	v_cvt_pk_bf16_f32 v120, v126, v127
	v_cvt_pk_bf16_f32 v121, v128, v129
	v_sub_f32_e32 v98, v98, v246
	v_sub_f32_e32 v99, v99, v246
	v_mfma_f32_32x32x16_bf16 v[50:65], v[82:85], v[118:121], v[50:65]
	v_mfma_f32_32x32x16_bf16 v[34:49], v[86:89], v[118:121], v[34:49]
	v_mfma_f32_32x32x16_bf16 v[18:33], v[90:93], v[118:121], v[18:33]
	v_mfma_f32_32x32x16_bf16 v[2:17], v[94:97], v[118:121], v[2:17]
	ds_read_b64_tr_b16 v[82:83], v170 offset:12304
	ds_read_b64_tr_b16 v[84:85], v170 offset:14352
	ds_read_b64_tr_b16 v[86:87], v171 offset:12304
	ds_read_b64_tr_b16 v[88:89], v171 offset:14352
	ds_read_b64_tr_b16 v[90:91], v172 offset:12304
	ds_read_b64_tr_b16 v[92:93], v172 offset:14352
	ds_read_b64_tr_b16 v[94:95], v173 offset:12304
	ds_read_b64_tr_b16 v[96:97], v173 offset:14352
	v_sub_f32_e32 v100, v100, v246
	v_sub_f32_e32 v101, v101, v246
	v_sub_f32_e32 v102, v102, v246
	v_sub_f32_e32 v103, v103, v246
	v_sub_f32_e32 v104, v104, v246
	v_sub_f32_e32 v105, v105, v246
	v_exp_f32_e32 v98, v98
	v_exp_f32_e32 v99, v99
	v_exp_f32_e32 v100, v100
	v_exp_f32_e32 v101, v101
	v_exp_f32_e32 v102, v102
	v_exp_f32_e32 v103, v103
	v_exp_f32_e32 v104, v104
	v_exp_f32_e32 v105, v105
	v_add_f32_e32 v240, v240, v98
	v_add_f32_e32 v241, v241, v99
	v_add_f32_e32 v240, v240, v100
	v_add_f32_e32 v241, v241, v101
	v_add_f32_e32 v240, v240, v102
	v_add_f32_e32 v241, v241, v103
	v_add_f32_e32 v240, v240, v104
	v_add_f32_e32 v241, v241, v105
	v_cvt_pk_bf16_f32 v98, v98, v99
	v_cvt_pk_bf16_f32 v99, v100, v101
	v_cvt_pk_bf16_f32 v100, v102, v103
	v_cvt_pk_bf16_f32 v101, v104, v105
	v_sub_f32_e32 v106, v106, v246
	v_sub_f32_e32 v107, v107, v246
	s_waitcnt lgkmcnt(8)
	v_mfma_f32_32x32x16_bf16 v[50:65], v[66:69], v[98:101], v[50:65]
	v_mfma_f32_32x32x16_bf16 v[34:49], v[70:73], v[98:101], v[34:49]
	v_mfma_f32_32x32x16_bf16 v[18:33], v[74:77], v[98:101], v[18:33]
	v_mfma_f32_32x32x16_bf16 v[2:17], v[78:81], v[98:101], v[2:17]
	v_sub_f32_e32 v108, v108, v246
	v_sub_f32_e32 v109, v109, v246
	v_sub_f32_e32 v110, v110, v246
	v_sub_f32_e32 v111, v111, v246
	v_sub_f32_e32 v112, v112, v246
	v_sub_f32_e32 v113, v113, v246
	v_exp_f32_e32 v106, v106
	v_exp_f32_e32 v107, v107
	v_exp_f32_e32 v108, v108
	v_exp_f32_e32 v109, v109
	v_exp_f32_e32 v110, v110
	v_exp_f32_e32 v111, v111
	v_exp_f32_e32 v112, v112
	v_exp_f32_e32 v113, v113
	v_add_f32_e32 v240, v240, v106
	v_add_f32_e32 v241, v241, v107
	v_add_f32_e32 v240, v240, v108
	v_add_f32_e32 v241, v241, v109
	v_add_f32_e32 v240, v240, v110
	v_add_f32_e32 v241, v241, v111
	v_add_f32_e32 v240, v240, v112
	v_add_f32_e32 v241, v241, v113
	v_cvt_pk_bf16_f32 v102, v106, v107
	v_cvt_pk_bf16_f32 v103, v108, v109
	v_cvt_pk_bf16_f32 v104, v110, v111
	v_cvt_pk_bf16_f32 v105, v112, v113
	v_add_f32_e32 v240, v240, v241
	v_add_f32_e32 v219, v219, v240
	s_waitcnt lgkmcnt(0)
	v_mfma_f32_32x32x16_bf16 v[50:65], v[82:85], v[102:105], v[50:65]
	v_mfma_f32_32x32x16_bf16 v[34:49], v[86:89], v[102:105], v[34:49]
	v_mfma_f32_32x32x16_bf16 v[18:33], v[90:93], v[102:105], v[18:33]
	v_mfma_f32_32x32x16_bf16 v[2:17], v[94:97], v[102:105], v[2:17]
.Lmoba_tail:
	s_andn2_b64 vcc, exec, s[14:15]
	s_cbranch_vccz .LBB0_759
	s_branch .LBB0_760

; #define MOBA_STORE(bb) do { LAS unsigned char* kd = lds + OFF_K + (bb) * 64 * KST + lrow * KST + lc * 32; *(LAS u32x4*)kd = rk0; *(LAS u32x4*)(kd + 16) = rk1; \
;         LAS unsigned char* vd = lds + OFF_V + (bb) * 64 * VST + lrow * VST + lc * 32; *(LAS u32x4*)vd = rv0; *(LAS u32x4*)(vd + 16) = rv1; } while (0)
; __device__ __forceinline__ void phase_moba_mfma(const Params& p, LAS unsigned char* lds, unsigned lds_base) {
;     ...
;             if (own) need = (kt * 64 <= 32 * wave + 31); else need = (__ballot((sel >> j) & 1u) != 0ull);
;             if (need) {
;     ...
;             if (nj >= 0) MOBA_STORE(buf ^ 1);
;             __syncthreads();
;             j = nj; kt = nkt; buf ^= 1;
.LBB0_758:
	v_mov_b32_e32 v1, v220
	s_cmp_eq_u32 s2, 0
	s_cbranch_scc1 .Lmoba_ret1
	s_add_i32 s0, s100, 3
	s_and_b32 s0, s0, 3
	s_mov_b32 s45, 1
	s_branch .Lmoba_pvblk

; #define MOBA_STORE(bb) do { LAS unsigned char* kd = lds + OFF_K + (bb) * 64 * KST + lrow * KST + lc * 32; *(LAS u32x4*)kd = rk0; *(LAS u32x4*)(kd + 16) = rk1; \
;         LAS unsigned char* vd = lds + OFF_V + (bb) * 64 * VST + lrow * VST + lc * 32; *(LAS u32x4*)vd = rv0; *(LAS u32x4*)(vd + 16) = rv1; } while (0)
; __device__ __forceinline__ void phase_moba_mfma(const Params& p, LAS unsigned char* lds, unsigned lds_base) {
;     ...
;             if (nj >= 0) MOBA_STORE(buf ^ 1);
;             __syncthreads();
.LBB0_759:
	s_cmp_lt_i32 s98, 0
	s_cbranch_scc1 .Lmoba_w0
	s_waitcnt vmcnt(4)
	s_branch .LBB0_760

; #define MOBA_STORE(bb) do { LAS unsigned char* kd = lds + OFF_K + (bb) * 64 * KST + lrow * KST + lc * 32; *(LAS u32x4*)kd = rk0; *(LAS u32x4*)(kd + 16) = rk1; \
;         LAS unsigned char* vd = lds + OFF_V + (bb) * 64 * VST + lrow * VST + lc * 32; *(LAS u32x4*)vd = rv0; *(LAS u32x4*)(vd + 16) = rv1; } while (0)
; __device__ __forceinline__ void phase_moba_mfma(const Params& p, LAS unsigned char* lds, unsigned lds_base) {
;     ...
;             if (nj >= 0) MOBA_STORE(buf ^ 1);
;             __syncthreads();
;             j = nj; kt = nkt; buf ^= 1;
;         }
.LBB0_760:
	s_andn2_b64 vcc, exec, s[12:13]
	s_waitcnt lgkmcnt(0)
	s_barrier
	s_cbranch_vccz .Lmoba_exit
	v_mov_b32_e32 v220, v1
	s_mov_b32 s19, s10
	s_mov_b32 s37, s11
	s_mov_b32 s10, s98
	s_mov_b32 s11, s99
	s_add_i32 s101, s101, 1
	s_cmp_eq_u32 s101, 3
	s_cselect_b32 s101, 0, s101
	s_add_i32 s100, s100, 1
	s_and_b32 s100, s100, 3
	s_branch .Lmoba_top
.Lmoba_exit:
	s_cmp_eq_u32 s2, 0
	s_cbranch_scc1 .LBB0_734
	s_mov_b32 s0, s100
	s_mov_b32 s45, 2
	s_branch .Lmoba_pvblk

; __global__ void __launch_bounds__(512, 2) fwd_megakernel(Params p) {
	.amdhsa_kernel _Z14fwd_megakernel6Params
		.amdhsa_group_segment_fixed_size 16
		.amdhsa_private_segment_fixed_size 0
		.amdhsa_kernarg_size 464
		.amdhsa_user_sgpr_count 2
		.amdhsa_user_sgpr_dispatch_ptr 0
		.amdhsa_user_sgpr_queue_ptr 0
		.amdhsa_user_sgpr_kernarg_segment_ptr 1
		.amdhsa_user_sgpr_dispatch_id 0
		.amdhsa_user_sgpr_kernarg_preload_length 0
		.amdhsa_user_sgpr_kernarg_preload_offset 0
		.amdhsa_user_sgpr_private_segment_size 0
		.amdhsa_uses_dynamic_stack 0
		.amdhsa_enable_private_segment 0
		.amdhsa_system_sgpr_workgroup_id_x 1
		.amdhsa_system_sgpr_workgroup_id_y 0
		.amdhsa_system_sgpr_workgroup_id_z 0
		.amdhsa_system_sgpr_workgroup_info 0
		.amdhsa_system_vgpr_workitem_id 2
		.amdhsa_next_free_vgpr 256
		.amdhsa_next_free_sgpr 102
		.amdhsa_accum_offset 256
		.amdhsa_reserve_vcc 1
		.amdhsa_float_round_mode_32 0
		.amdhsa_float_round_mode_16_64 0
		.amdhsa_float_denorm_mode_32 3
		.amdhsa_float_denorm_mode_16_64 3
		.amdhsa_dx10_clamp 1
		.amdhsa_ieee_mode 1
		.amdhsa_fp16_overflow 0
		.amdhsa_tg_split 0
		.amdhsa_exception_fp_ieee_invalid_op 0
		.amdhsa_exception_fp_denorm_src 0
		.amdhsa_exception_fp_ieee_div_zero 0
		.amdhsa_exception_fp_ieee_overflow 0
		.amdhsa_exception_fp_ieee_underflow 0
		.amdhsa_exception_fp_ieee_inexact 0
		.amdhsa_exception_int_div_zero 0
	.end_amdhsa_kernel

; __global__ void __launch_bounds__(512, 2) fwd_megakernel(Params p) {
amdhsa.kernels:
  - .agpr_count:     0
    .args:
      - .offset:         0
        .size:           208
        .value_kind:     by_value
      - .offset:         208
        .size:           4
        .value_kind:     hidden_block_count_x
      - .offset:         212
        .size:           4
        .value_kind:     hidden_block_count_y
      - .offset:         216
        .size:           4
        .value_kind:     hidden_block_count_z
      - .offset:         220
        .size:           2
        .value_kind:     hidden_group_size_x
      - .offset:         222
        .size:           2
        .value_kind:     hidden_group_size_y
      - .offset:         224
        .size:           2
        .value_kind:     hidden_group_size_z
      - .offset:         226
        .size:           2
        .value_kind:     hidden_remainder_x
      - .offset:         228
        .size:           2
        .value_kind:     hidden_remainder_y
      - .offset:         230
        .size:           2
        .value_kind:     hidden_remainder_z
      - .offset:         248
        .size:           8
        .value_kind:     hidden_global_offset_x
      - .offset:         256
        .size:           8
        .value_kind:     hidden_global_offset_y
      - .offset:         264
        .size:           8
        .value_kind:     hidden_global_offset_z
      - .offset:         272
        .size:           2
        .value_kind:     hidden_grid_dims
      - .offset:         296
        .size:           8
        .value_kind:     hidden_multigrid_sync_arg
      - .offset:         328
        .size:           4
        .value_kind:     hidden_dynamic_lds_size
    .group_segment_fixed_size: 16
    .kernarg_segment_align: 8
    .kernarg_segment_size: 464
    .language:       OpenCL C
    .language_version:
      - 2
      - 0
    .max_flat_workgroup_size: 512
    .name:           _Z14fwd_megakernel6Params
    .private_segment_fixed_size: 0
    .sgpr_count:     108
    .sgpr_spill_count: 137
    .symbol:         _Z14fwd_megakernel6Params.kd
    .uniform_work_group_size: 1
    .uses_dynamic_stack: false
    .vgpr_count:     256
    .vgpr_spill_count: 0
    .wavefront_size: 64
